# non-temporal hint also on the ffn_w_in f32 weight loads of phase 9 (two load groups the first pass missed)
# speedup vs baseline: 1.0157x; 1.0017x over previous
; __device__ __forceinline__ int opaque_tid() { int t = (int)threadIdx.x; asm volatile("" : "+v"(t)); return t; }
; __device__ __forceinline__ int wt_remap(int grp, int t) { return (grp == 2) ? (t < 768 ? t : t + 512) : t; }
; __device__ __forceinline__ void wt_load(const WtDesc& d, int tid, f32x4 (&v)[8]) {
;     const int r = tid >> 6, c4 = tid & 63; const int col = (c4 < 32) ? d.ns0 + 4 * c4 : d.ns1 + 4 * (c4 - 32);
; #pragma unroll
;     for (int i = 0; i < 8; ++i) v[i] = *(const f32x4*)(d.W + (size_t)(d.k0 + r + 8 * i) * d.ldw + col);
; }
; __device__ void wt_run(const Params& p, int grp, int first, int stride, int ntiles, unsigned char* smem_g) {
;     constexpr int LD = 260;
;     float* tile = (float*)smem_g;
;     const int tid = opaque_tid();
;     int tl = first;
;     if (tl >= ntiles) return;
;     const int dg = (grp == 2) ? 0 : grp;
;     WtDesc cur = wt_decode(p, dg, wt_remap(grp, tl)); f32x4 v[8];
;     wt_load(cur, tid, v);
.LBB0_73:
	s_or_b64 exec, exec, s[2:3]
	v_readlane_b32 s0, v251, 15
	v_readlane_b32 s1, v251, 16
	v_mov_b32_e32 v2, v212
	s_andn2_b64 vcc, exec, s[0:1]
	s_cbranch_vccnz .LBB0_78
	v_and_b32_e32 v0, 63, v2
	v_lshlrev_b32_e32 v1, 2, v0
	s_waitcnt vmcnt(0)
	v_or_b32_e32 v4, 0x1500, v1
	v_cmp_gt_u32_e32 vcc, 32, v0
	v_readlane_b32 s0, v251, 18
	v_readlane_b32 s36, v253, 33
	v_cndmask_b32_e32 v0, v4, v1, vcc
	v_add_u32_e32 v4, s0, v0
	v_ashrrev_i32_e32 v1, 6, v2
	v_readlane_b32 s3, v251, 17
	v_readlane_b32 s50, v253, 47
	v_readlane_b32 s51, v253, 48
	v_ashrrev_i32_e32 v5, 31, v4
	v_add_u32_e32 v6, s3, v1
	v_mov_b64_e32 v[28:29], s[50:51]
	s_mov_b32 s2, 0xac00
	v_mad_i64_i32 v[6:7], s[0:1], v6, s2, v[28:29]
	v_lshlrev_b64 v[30:31], 2, v[4:5]
	v_add_u32_e32 v36, 8, v1
	v_add_u32_e32 v37, 16, v1
	v_add_u32_e32 v38, 24, v1
	v_add_u32_e32 v39, 32, v1
	v_add_u32_e32 v40, 40, v1
	v_add_u32_e32 v41, 48, v1
	v_add_u32_e32 v42, 56, v1
	v_lshl_add_u64 v[4:5], v[6:7], 0, v[30:31]
	v_add_u32_e32 v6, s3, v36
	v_add_u32_e32 v12, s3, v37
	v_add_u32_e32 v14, s3, v38
	v_add_u32_e32 v20, s3, v39
	v_add_u32_e32 v22, s3, v40
	v_add_u32_e32 v32, s3, v41
	v_add_u32_e32 v34, s3, v42
	v_mad_i64_i32 v[6:7], s[0:1], v6, s2, v[28:29]
	v_mad_i64_i32 v[12:13], s[0:1], v12, s2, v[28:29]
	v_mad_i64_i32 v[14:15], s[0:1], v14, s2, v[28:29]
	v_mad_i64_i32 v[20:21], s[0:1], v20, s2, v[28:29]
	v_mad_i64_i32 v[22:23], s[0:1], v22, s2, v[28:29]
	v_mad_i64_i32 v[32:33], s[0:1], v32, s2, v[28:29]
	v_mad_i64_i32 v[28:29], s[0:1], v34, s2, v[28:29]
	v_lshl_add_u64 v[8:9], v[6:7], 0, v[30:31]
	v_lshl_add_u64 v[12:13], v[12:13], 0, v[30:31]
	v_lshl_add_u64 v[16:17], v[14:15], 0, v[30:31]
	v_lshl_add_u64 v[20:21], v[20:21], 0, v[30:31]
	v_lshl_add_u64 v[24:25], v[22:23], 0, v[30:31]
	v_lshl_add_u64 v[32:33], v[32:33], 0, v[30:31]
	v_lshl_add_u64 v[34:35], v[28:29], 0, v[30:31]
	global_load_dwordx4 v[4:7], v[4:5], off nt
	s_nop 0
	global_load_dwordx4 v[8:11], v[8:9], off nt
	s_nop 0
	global_load_dwordx4 v[12:15], v[12:13], off nt
	s_nop 0
	global_load_dwordx4 v[16:19], v[16:17], off nt
	s_nop 0
	global_load_dwordx4 v[20:23], v[20:21], off nt
	s_nop 0
	global_load_dwordx4 v[24:27], v[24:25], off nt
	s_nop 0
	global_load_dwordx4 v[28:31], v[32:33], off nt
	s_nop 0
	global_load_dwordx4 v[32:35], v[34:35], off nt
	v_lshlrev_b32_e32 v43, 4, v2
	v_and_b32_e32 v43, 0x3f0, v43
	v_add_u32_e32 v44, 0, v43
	v_ashrrev_i32_e32 v43, 1, v2
	v_lshlrev_b32_e32 v2, 5, v2
	v_readlane_b32 s44, v253, 41
	v_readlane_b32 s45, v253, 42
	v_and_b32_e32 v2, 32, v2
	s_movk_i32 s0, 0x410
	v_readlane_b32 s38, v253, 35
	v_readlane_b32 s48, v253, 45
	v_readlane_b32 s49, v253, 46
	s_mov_b32 s44, 0x6dc9c883
	v_lshl_add_u32 v45, v43, 2, 0
	v_mul_lo_u32 v46, v1, s0
	v_mul_u32_u24_e32 v47, 0x410, v2
	v_readlane_b32 s10, v251, 19
	v_readlane_b32 s38, v254, 19
	s_mov_b32 s49, 0xf149f2ca
	s_movk_i32 s48, 0x3000
	s_mov_b32 s45, 0x3fc45f30
	v_add_u32_e32 v44, v44, v46
	v_lshlrev_b32_e32 v2, 1, v2
	v_add_u32_e32 v45, v45, v47
	v_readlane_b32 s2, v253, 56
	s_mov_b32 s18, s3
	s_mov_b32 s3, s34
	s_mov_b32 s8, s10
	v_readlane_b32 s37, v253, 34
	v_readlane_b32 s39, v253, 36
	v_readlane_b32 s40, v253, 37
	v_readlane_b32 s41, v253, 38
	v_readlane_b32 s42, v253, 39
	v_readlane_b32 s43, v253, 40
	v_readlane_b32 s46, v253, 43
	v_readlane_b32 s47, v253, 44
	s_branch .LBB0_76

; __device__ __forceinline__ int wt_remap(int grp, int t) { return (grp == 2) ? (t < 768 ? t : t + 512) : t; }
; __device__ __forceinline__ void wt_load(const WtDesc& d, int tid, f32x4 (&v)[8]) {
;     const int r = tid >> 6, c4 = tid & 63; const int col = (c4 < 32) ? d.ns0 + 4 * c4 : d.ns1 + 4 * (c4 - 32);
; #pragma unroll
;     for (int i = 0; i < 8; ++i) v[i] = *(const f32x4*)(d.W + (size_t)(d.k0 + r + 8 * i) * d.ldw + col);
; }
; __device__ void wt_run(const Params& p, int grp, int first, int stride, int ntiles, unsigned char* smem_g) {
;     ...
;     for (;;) {
;         { const int r = tid >> 6, c4 = tid & 63;
; #pragma unroll
;           for (int i = 0; i < 8; ++i) *(f32x4*)(tile + (r + 8 * i) * LD + 4 * c4) = v[i]; }
;         const int nxt = tl + stride; const bool has = nxt < ntiles;
;         WtDesc nd = cur;
;         if (has) { nd = wt_decode(p, dg, wt_remap(grp, nxt)); wt_load(nd, tid, v); }
.LBB0_76:
	s_add_i32 s3, s3, s60
	s_cmpk_gt_i32 s3, 0x55f
	s_cselect_b64 s[0:1], -1, 0
	s_and_b64 vcc, exec, s[0:1]
	s_mov_b32 s9, s18
	s_waitcnt vmcnt(0)
	ds_write_b128 v44, v[4:7]
	ds_write_b128 v44, v[8:11] offset:8320
	ds_write_b128 v44, v[12:15] offset:16640
	ds_write_b128 v44, v[16:19] offset:24960
	ds_write_b128 v44, v[20:23] offset:33280
	ds_write_b128 v44, v[24:27] offset:41600
	ds_write_b128 v44, v[28:31] offset:49920
	ds_write_b128 v44, v[32:35] offset:58240
	s_cbranch_vccnz .LBB0_75
	s_ashr_i32 s8, s3, 5
	v_readlane_b32 s36, v253, 33
	s_and_b32 s9, s2, 0x7c0
	v_lshl_add_u32 v4, s8, 7, v0
	v_readlane_b32 s50, v253, 47
	v_readlane_b32 s51, v253, 48
	v_ashrrev_i32_e32 v5, 31, v4
	v_add_u32_e32 v6, s9, v1
	v_mov_b64_e32 v[28:29], s[50:51]
	s_mov_b32 s11, 0xac00
	v_mad_i64_i32 v[6:7], s[12:13], v6, s11, v[28:29]
	v_lshlrev_b64 v[30:31], 2, v[4:5]
	v_lshl_add_u64 v[4:5], v[6:7], 0, v[30:31]
	v_add_u32_e32 v6, s9, v36
	v_add_u32_e32 v12, s9, v37
	v_add_u32_e32 v14, s9, v38
	v_add_u32_e32 v20, s9, v39
	v_add_u32_e32 v22, s9, v40
	v_add_u32_e32 v32, s9, v41
	v_add_u32_e32 v34, s9, v42
	v_mad_i64_i32 v[6:7], s[12:13], v6, s11, v[28:29]
	v_mad_i64_i32 v[12:13], s[12:13], v12, s11, v[28:29]
	v_mad_i64_i32 v[14:15], s[12:13], v14, s11, v[28:29]
	v_mad_i64_i32 v[20:21], s[12:13], v20, s11, v[28:29]
	v_mad_i64_i32 v[22:23], s[12:13], v22, s11, v[28:29]
	v_mad_i64_i32 v[32:33], s[12:13], v32, s11, v[28:29]
	v_mad_i64_i32 v[28:29], s[12:13], v34, s11, v[28:29]
	v_lshl_add_u64 v[8:9], v[6:7], 0, v[30:31]
	v_lshl_add_u64 v[12:13], v[12:13], 0, v[30:31]
	v_lshl_add_u64 v[16:17], v[14:15], 0, v[30:31]
	v_lshl_add_u64 v[20:21], v[20:21], 0, v[30:31]
	v_lshl_add_u64 v[24:25], v[22:23], 0, v[30:31]
	v_lshl_add_u64 v[32:33], v[32:33], 0, v[30:31]
	v_lshl_add_u64 v[34:35], v[28:29], 0, v[30:31]
	global_load_dwordx4 v[4:7], v[4:5], off nt
	s_nop 0
	global_load_dwordx4 v[8:11], v[8:9], off nt
	s_nop 0
	global_load_dwordx4 v[12:15], v[12:13], off nt
	s_nop 0
	global_load_dwordx4 v[16:19], v[16:17], off nt
	s_nop 0
	global_load_dwordx4 v[20:23], v[20:21], off nt
	s_nop 0
	global_load_dwordx4 v[24:27], v[24:25], off nt
	s_nop 0
	global_load_dwordx4 v[28:31], v[32:33], off nt
	s_nop 0
	global_load_dwordx4 v[32:35], v[34:35], off nt
	v_readlane_b32 s44, v253, 41
	v_readlane_b32 s45, v253, 42
	v_readlane_b32 s38, v253, 35
	v_readlane_b32 s48, v253, 45
	v_readlane_b32 s49, v253, 46
	s_mov_b32 s44, 0x6dc9c883
	v_readlane_b32 s38, v254, 19
	s_mov_b32 s49, 0xf149f2ca
	s_movk_i32 s48, 0x3000
	s_mov_b32 s45, 0x3fc45f30
	s_lshl_b32 s8, s8, 8
	v_readlane_b32 s37, v253, 34
	v_readlane_b32 s39, v253, 36
	v_readlane_b32 s40, v253, 37
	v_readlane_b32 s41, v253, 38
	v_readlane_b32 s42, v253, 39
	v_readlane_b32 s43, v253, 40
	v_readlane_b32 s46, v253, 43
	v_readlane_b32 s47, v253, 44
	s_branch .LBB0_75
